# NSA cmp/sel/window loops: packed v_pk_add/mul/fma_f32 beside MFMAs split into scalar f32 pairs (bit-identical)
# speedup vs baseline: 1.0143x; 1.0143x over previous
.LBB0_381:
	s_add_i32 s6, s20, -3
	s_ashr_i32 s7, s6, 31
	s_lshl_b64 s[8:9], s[6:7], 10
	v_lshl_add_u64 v[96:97], v[140:141], 0, s[8:9]
	global_load_dwordx4 v[112:115], v[96:97], off
	s_add_i32 s8, s20, -1
	s_ashr_i32 s9, s8, 31
	s_lshl_b64 s[10:11], s[8:9], 10
	v_lshl_add_u64 v[98:99], v[140:141], 0, s[10:11]
	global_load_dwordx4 v[108:111], v[98:99], off
	global_load_dwordx4 v[116:119], v[96:97], off offset:1024
	global_load_dwordx4 v[104:107], v[98:99], off offset:1024
	v_or_b32_e32 v160, 31, v153
	v_or_b32_e32 v176, 47, v153
	v_add_u32_e32 v120, 64, v154
	v_sub_u32_e32 v124, v134, v160
	v_sub_u32_e32 v125, v134, v176
	v_cvt_f32_i32_e32 v208, v120
	v_cvt_f32_i32_e32 v209, v124
	v_cvt_f32_i32_e32 v210, v125
	v_or_b32_e32 v159, 0x5f, v153
	v_or_b32_e32 v161, 0x6f, v153
	v_or_b32_e32 v177, 0x7f, v153
	v_or_b32_e32 v186, 63, v153
	v_sub_u32_e32 v175, v134, v159
	v_sub_u32_e32 v174, v134, v186
	v_sub_u32_e32 v178, v134, v161
	v_sub_u32_e32 v179, v134, v177
	v_cvt_f32_i32_e32 v212, v175
	v_cvt_f32_i32_e32 v180, v154
	v_cvt_f32_i32_e32 v211, v174
	v_cvt_f32_i32_e32 v213, v178
	v_cvt_f32_i32_e32 v214, v179
	s_mov_b32 s7, s49
	s_lshl_b64 s[6:7], s[6:7], 10
	s_add_i32 s48, s20, -2
	v_lshl_add_u64 v[96:97], v[150:151], 0, s[6:7]
	s_lshl_b64 s[6:7], s[48:49], 10
	s_mov_b32 s9, s49
	v_lshl_add_u64 v[100:101], v[150:151], 0, s[6:7]
	v_add_u32_e32 v157, 0x4f, v153
	v_add_u32_e32 v158, 0x8f, v153
	s_lshl_b64 s[6:7], s[8:9], 10
	v_cmp_gt_i32_e64 s[12:13], v159, v129
	v_cmp_gt_i32_e64 s[14:15], v160, v134
	s_mov_b32 s21, s49
	v_lshl_add_u64 v[174:175], v[150:151], 0, s[6:7]
	v_cmp_gt_i32_e64 s[16:17], v161, v129
	v_cmp_gt_i32_e64 s[18:19], v176, v134
	v_cmp_gt_i32_e32 vcc, v177, v129
	v_cmp_gt_i32_e64 s[6:7], v186, v134
	v_cmp_gt_i32_e64 s[8:9], v158, v129
	v_cmp_gt_i32_e64 s[10:11], v157, v134
	s_lshl_b64 s[24:25], s[20:21], 10
	global_load_dwordx4 v[96:99], v[96:97], off
	s_waitcnt vmcnt(3)
	v_mfma_f32_16x16x32_bf16 v[124:127], v[108:111], v[0:3], 0
	global_load_dwordx4 v[100:103], v[100:101], off
	v_mfma_f32_16x16x32_bf16 v[120:123], v[112:115], v[0:3], 0
	s_waitcnt vmcnt(3)
	v_mfma_f32_16x16x32_bf16 v[120:123], v[116:119], v[4:7], v[120:123]
	s_waitcnt vmcnt(2)
	v_mfma_f32_16x16x32_bf16 v[124:127], v[104:107], v[4:7], v[124:127]
	s_nop 5
	v_add_f32_e32 v120, 0xc1800000, v120
	s_nop 0
	v_add_f32_e32 v124, 0xc1800000, v124
	v_add_f32_e32 v121, 0xc1800000, v121
	v_add_f32_e32 v122, 0xc1800000, v122
	v_add_f32_e32 v123, 0xc1800000, v123
	v_add_f32_e32 v125, 0xc1800000, v125
	v_add_f32_e32 v126, 0xc1800000, v126
	v_add_f32_e32 v127, 0xc1800000, v127
	v_fma_f32 v120, -v170, v209, v120
	v_fma_f32 v124, -v170, v212, v124
	v_fma_f32 v123, -v170, v208, v123
	v_fma_f32 v127, -v170, v180, v127
	v_fma_f32 v121, -v170, v210, v121
	v_fma_f32 v122, -v170, v211, v122
	v_fma_f32 v125, -v170, v213, v125
	v_fma_f32 v126, -v170, v214, v126
	v_exp_f32_e32 v120, v120
	v_exp_f32_e32 v124, v124
	v_exp_f32_e32 v123, v123
	v_exp_f32_e32 v127, v127
	v_exp_f32_e32 v121, v121
	v_exp_f32_e32 v122, v122
	v_exp_f32_e32 v125, v125
	v_exp_f32_e32 v126, v126
	v_cndmask_b32_e64 v179, v124, 0, s[12:13]
	v_cndmask_b32_e64 v178, v120, 0, s[14:15]
	v_cndmask_b32_e64 v185, v125, 0, s[16:17]
	v_cndmask_b32_e64 v184, v121, 0, s[18:19]
	v_cndmask_b32_e64 v187, v126, 0, vcc
	v_cndmask_b32_e64 v186, v122, 0, s[6:7]
	v_cndmask_b32_e64 v189, v127, 0, s[8:9]
	v_cndmask_b32_e64 v188, v123, 0, s[10:11]
	v_mul_f32_e32 v120, v142, v178
	v_mul_f32_e32 v121, v143, v179
	v_mul_f32_e32 v122, v142, v184
	v_mul_f32_e32 v123, v143, v185
	v_mul_f32_e32 v124, v142, v186
	v_mul_f32_e32 v125, v143, v187
	v_mul_f32_e32 v126, v142, v188
	v_mul_f32_e32 v127, v143, v189
	v_cvt_pk_bf16_f32 v158, v120, v122
	v_cvt_pk_bf16_f32 v160, v121, v123
	v_lshl_add_u64 v[120:121], v[150:151], 0, s[24:25]
	v_cvt_pk_bf16_f32 v159, v124, v126
	v_cvt_pk_bf16_f32 v161, v125, v127
	global_load_dwordx4 v[124:127], v[174:175], off
	s_waitcnt vmcnt(2)
	v_mfma_f32_16x16x32_bf16 v[92:95], v[96:99], v[158:161], v[92:95]
	global_load_dwordx4 v[120:123], v[120:121], off
	s_waitcnt vmcnt(2)
	v_mfma_f32_16x16x32_bf16 v[88:91], v[100:103], v[158:161], v[88:91]
	v_mfma_f32_16x16x32_bf16 v[174:177], v[108:111], v[8:11], 0
	s_waitcnt vmcnt(1)
	v_mfma_f32_16x16x32_bf16 v[84:87], v[124:127], v[158:161], v[84:87]
	s_waitcnt vmcnt(0)
	v_mfma_f32_16x16x32_bf16 v[80:83], v[120:123], v[158:161], v[80:83]
	v_mfma_f32_16x16x32_bf16 v[158:161], v[112:115], v[8:11], 0
	v_mfma_f32_16x16x32_bf16 v[158:161], v[116:119], v[12:15], v[158:161]
	s_nop 7
	v_add_f32_e32 v157, 0xc1800000, v158
	v_add_f32_e32 v158, 0xc1800000, v159
	v_fma_f32 v158, -v171, v210, v158
	v_exp_f32_e32 v192, v158
	v_add_f32_e32 v158, 0xc1800000, v160
	v_fma_f32 v158, -v171, v211, v158
	v_exp_f32_e32 v194, v158
	v_add_f32_e32 v158, 0xc1800000, v161
	v_fma_f32 v158, -v171, v208, v158
	v_exp_f32_e32 v196, v158
	v_mfma_f32_16x16x32_bf16 v[158:161], v[104:107], v[12:15], v[174:177]
	v_fma_f32 v157, -v171, v209, v157
	v_exp_f32_e32 v157, v157
	v_cndmask_b32_e64 v194, v194, 0, s[6:7]
	v_cndmask_b32_e64 v192, v192, 0, s[18:19]
	v_cndmask_b32_e64 v196, v196, 0, s[10:11]
	s_nop 2
	v_add_f32_e32 v158, 0xc1800000, v158
	v_fma_f32 v158, -v171, v212, v158
	v_exp_f32_e32 v158, v158
	v_cndmask_b32_e64 v190, v157, 0, s[14:15]
	v_add_f32_e32 v157, 0xc1800000, v160
	v_add_f32_e32 v159, 0xc1800000, v159
	v_cndmask_b32_e64 v191, v158, 0, s[12:13]
	v_fma_f32 v157, -v171, v214, v157
	v_add_f32_e32 v158, 0xc1800000, v161
	v_fma_f32 v159, -v171, v213, v159
	v_exp_f32_e32 v157, v157
	v_fma_f32 v158, -v171, v180, v158
	v_exp_f32_e32 v159, v159
	v_exp_f32_e32 v158, v158
	v_cndmask_b32_e64 v195, v157, 0, vcc
	v_mul_f32_e32 v160, v144, v194
	v_mul_f32_e32 v161, v145, v195
	v_cndmask_b32_e64 v193, v159, 0, s[16:17]
	v_cndmask_b32_e64 v197, v158, 0, s[8:9]
	v_mul_f32_e32 v174, v144, v190
	v_mul_f32_e32 v175, v145, v191
	v_mul_f32_e32 v176, v144, v192
	v_mul_f32_e32 v177, v145, v193
	v_mul_f32_e32 v198, v144, v196
	v_mul_f32_e32 v199, v145, v197
	v_cvt_pk_bf16_f32 v158, v174, v176
	s_nop 0
	v_cvt_pk_bf16_f32 v159, v160, v198
	v_cvt_pk_bf16_f32 v160, v175, v177
	v_cvt_pk_bf16_f32 v161, v161, v199
	v_mfma_f32_16x16x32_bf16 v[174:177], v[108:111], v[16:19], 0
	v_mfma_f32_16x16x32_bf16 v[76:79], v[96:99], v[158:161], v[76:79]
	v_mfma_f32_16x16x32_bf16 v[72:75], v[100:103], v[158:161], v[72:75]
	v_mfma_f32_16x16x32_bf16 v[68:71], v[124:127], v[158:161], v[68:71]
	v_mfma_f32_16x16x32_bf16 v[64:67], v[120:123], v[158:161], v[64:67]
	v_mfma_f32_16x16x32_bf16 v[158:161], v[112:115], v[16:19], 0
	v_mfma_f32_16x16x32_bf16 v[158:161], v[116:119], v[20:23], v[158:161]
	v_mfma_f32_16x16x32_bf16 v[108:111], v[108:111], v[24:27], 0
	v_mfma_f32_16x16x32_bf16 v[112:115], v[112:115], v[24:27], 0
	s_nop 5
	v_add_f32_e32 v157, 0xc1800000, v158
	v_add_f32_e32 v158, 0xc1800000, v159
	v_fma_f32 v158, -v172, v210, v158
	v_exp_f32_e32 v198, v158
	v_add_f32_e32 v158, 0xc1800000, v160
	v_fma_f32 v158, -v172, v211, v158
	v_exp_f32_e32 v202, v158
	v_add_f32_e32 v158, 0xc1800000, v161
	v_fma_f32 v158, -v172, v208, v158
	v_exp_f32_e32 v204, v158
	v_mfma_f32_16x16x32_bf16 v[158:161], v[104:107], v[20:23], v[174:177]
	v_fma_f32 v157, -v172, v209, v157
	v_exp_f32_e32 v157, v157
	v_cndmask_b32_e64 v202, v202, 0, s[6:7]
	v_mfma_f32_16x16x32_bf16 v[104:107], v[104:107], v[28:31], v[108:111]
	v_cndmask_b32_e64 v198, v198, 0, s[18:19]
	s_nop 2
	v_add_f32_e32 v158, 0xc1800000, v158
	v_fma_f32 v158, -v172, v212, v158
	v_mfma_f32_16x16x32_bf16 v[112:115], v[116:119], v[28:31], v[112:115]
	v_exp_f32_e32 v158, v158
	v_add_f32_e32 v104, 0xc1800000, v104
	v_cndmask_b32_e64 v174, v157, 0, s[14:15]
	v_add_f32_e32 v157, 0xc1800000, v160
	v_fma_f32 v104, -v173, v212, v104
	s_nop 2
	v_add_f32_e32 v113, 0xc1800000, v113
	v_add_f32_e32 v105, 0xc1800000, v105
	v_fma_f32 v157, -v172, v214, v157
	v_fma_f32 v113, -v173, v210, v113
	v_exp_f32_e32 v104, v104
	v_fma_f32 v105, -v173, v213, v105
	v_exp_f32_e32 v157, v157
	v_exp_f32_e32 v116, v113
	v_add_f32_e32 v113, 0xc1800000, v114
	v_exp_f32_e32 v105, v105
	v_add_f32_e32 v159, 0xc1800000, v159
	v_cndmask_b32_e64 v175, v158, 0, s[12:13]
	v_add_f32_e32 v158, 0xc1800000, v161
	v_fma_f32 v113, -v173, v211, v113
	v_fma_f32 v159, -v172, v213, v159
	v_fma_f32 v158, -v172, v180, v158
	v_exp_f32_e32 v118, v113
	v_add_f32_e32 v113, 0xc1800000, v115
	v_exp_f32_e32 v159, v159
	v_exp_f32_e32 v158, v158
	v_add_f32_e32 v112, 0xc1800000, v112
	v_fma_f32 v113, -v173, v208, v113
	v_cndmask_b32_e64 v109, v104, 0, s[12:13]
	v_add_f32_e32 v104, 0xc1800000, v106
	v_cndmask_b32_e64 v203, v157, 0, vcc
	v_fma_f32 v112, -v173, v209, v112
	v_exp_f32_e32 v157, v113
	v_cndmask_b32_e64 v113, v105, 0, s[16:17]
	v_fma_f32 v104, -v173, v214, v104
	v_add_f32_e32 v105, 0xc1800000, v107
	v_exp_f32_e32 v112, v112
	v_exp_f32_e32 v104, v104
	v_fma_f32 v105, -v173, v180, v105
	v_exp_f32_e32 v105, v105
	v_cndmask_b32_e64 v199, v159, 0, s[16:17]
	v_mul_f32_e32 v160, v146, v202
	v_mul_f32_e32 v161, v147, v203
	v_cndmask_b32_e64 v205, v158, 0, s[8:9]
	v_cndmask_b32_e64 v204, v204, 0, s[10:11]
	v_mul_f32_e32 v176, v146, v174
	v_mul_f32_e32 v177, v147, v175
	v_mul_f32_e32 v200, v146, v198
	v_mul_f32_e32 v201, v147, v199
	v_mul_f32_e32 v206, v146, v204
	v_mul_f32_e32 v207, v147, v205
	v_cvt_pk_bf16_f32 v158, v176, v200
	v_cndmask_b32_e64 v108, v112, 0, s[14:15]
	v_cvt_pk_bf16_f32 v159, v160, v206
	v_cvt_pk_bf16_f32 v160, v177, v201
	v_cvt_pk_bf16_f32 v161, v161, v207
	v_fma_f32 v176, v142, v178, 0
	v_fma_f32 v177, v143, v179, 0
	v_mfma_f32_16x16x32_bf16 v[60:63], v[96:99], v[158:161], v[60:63]
	v_cndmask_b32_e64 v112, v116, 0, s[18:19]
	v_cndmask_b32_e64 v117, v104, 0, vcc
	v_cndmask_b32_e64 v116, v118, 0, s[6:7]
	v_mfma_f32_16x16x32_bf16 v[56:59], v[100:103], v[158:161], v[56:59]
	v_fma_f32 v176, v144, v190, v176
	v_fma_f32 v177, v145, v191, v177
	v_mul_f32_e32 v106, v148, v116
	v_mul_f32_e32 v107, v149, v117
	v_cndmask_b32_e64 v119, v105, 0, s[8:9]
	v_mfma_f32_16x16x32_bf16 v[52:55], v[124:127], v[158:161], v[52:55]
	v_cndmask_b32_e64 v118, v157, 0, s[10:11]
	v_fma_f32 v178, v142, v184, 0
	v_fma_f32 v179, v143, v185, 0
	v_mul_f32_e32 v110, v148, v108
	v_mul_f32_e32 v111, v149, v109
	v_mfma_f32_16x16x32_bf16 v[48:51], v[120:123], v[158:161], v[48:51]
	v_fma_f32 v160, v142, v188, 0
	v_fma_f32 v161, v143, v189, 0
	v_fma_f32 v158, v142, v186, 0
	v_fma_f32 v159, v143, v187, 0
	v_fma_f32 v160, v144, v196, v160
	v_fma_f32 v161, v145, v197, v161
	v_mul_f32_e32 v114, v148, v112
	v_mul_f32_e32 v115, v149, v113
	v_mul_f32_e32 v184, v148, v118
	v_mul_f32_e32 v185, v149, v119
	v_cvt_pk_bf16_f32 v104, v110, v114
	v_fma_f32 v178, v144, v192, v178
	v_fma_f32 v179, v145, v193, v179
	v_cvt_pk_bf16_f32 v105, v106, v184
	v_cvt_pk_bf16_f32 v106, v111, v115
	v_cvt_pk_bf16_f32 v107, v107, v185
	v_fma_f32 v158, v144, v194, v158
	v_fma_f32 v159, v145, v195, v159
	v_mfma_f32_16x16x32_bf16 v[44:47], v[96:99], v[104:107], v[44:47]
	v_fma_f32 v96, v146, v174, v176
	v_fma_f32 v97, v147, v175, v177
	v_fma_f32 v98, v146, v198, v178
	v_fma_f32 v99, v147, v199, v179
	v_fma_f32 v110, v146, v202, v158
	v_fma_f32 v111, v147, v203, v159
	v_mfma_f32_16x16x32_bf16 v[40:43], v[100:103], v[104:107], v[40:43]
	v_fma_f32 v100, v146, v204, v160
	v_fma_f32 v101, v147, v205, v161
	v_fma_f32 v102, v148, v108, v96
	v_fma_f32 v103, v149, v109, v97
	v_fma_f32 v96, v148, v118, v100
	v_fma_f32 v97, v149, v119, v101
	ds_read_b64 v[100:101], v155
	v_fma_f32 v98, v148, v112, v98
	v_fma_f32 v99, v149, v113, v99
	v_fma_f32 v108, v148, v116, v110
	v_fma_f32 v109, v149, v117, v111
	v_add_f32_e32 v98, v102, v98
	v_add_f32_e32 v99, v103, v99
	v_add_f32_e32 v102, v108, v96
	v_add_f32_e32 v103, v109, v97
	v_mfma_f32_16x16x32_bf16 v[36:39], v[124:127], v[104:107], v[36:39]
	v_add_f32_e64 v98, v98, v102
	v_add_f32_e64 v99, v99, v103
	v_cmp_gt_i32_e32 vcc, 63, v156
	s_waitcnt lgkmcnt(0)
	v_add_f32_e32 v98, v98, v100
	v_add_f32_e32 v99, v99, v101
	v_mfma_f32_16x16x32_bf16 v[32:35], v[120:123], v[104:107], v[32:35]
	ds_write_b64 v155, v[98:99]
	s_waitcnt lgkmcnt(0)
	s_and_saveexec_b64 s[6:7], vcc
	s_cbranch_execz .LBB0_383
	ds_read_b32 v98, v155 offset:4
	s_waitcnt lgkmcnt(0)
	v_add_f32_e32 v96, v96, v98
	ds_write_b32 v155, v96 offset:4

.LBB0_398:
	s_lshr_b32 s8, s26, 1
	s_sub_i32 s9, s8, 32
	s_cmp_lt_u32 s26, 64
	s_cselect_b64 vcc, -1, 0
	s_and_b64 s[6:7], vcc, exec
	s_cselect_b32 s6, s8, s9
	v_cndmask_b32_e32 v96, v141, v140, vcc
	s_lshl_b32 s6, 1, s6
	v_and_b32_e32 v96, s6, v96
	v_cmp_ne_u32_e64 s[8:9], 0, v96
	s_mov_b64 vcc, s[8:9]
	s_cbranch_vccz .LBB0_397
	v_add_u32_e32 v152, s1, v130
	s_waitcnt vmcnt(0)
	ds_read_b128 v[124:127], v252 offset:4096
	ds_read_b128 v[120:123], v252 offset:5120
	ds_read_b128 v[116:119], v252 offset:6144
	ds_read_b128 v[112:115], v252 offset:7168
	ds_read_b128 v[108:111], v252 offset:8192
	ds_read_b128 v[104:107], v252 offset:9216
	ds_read_b128 v[100:103], v252 offset:10240
	ds_read_b128 v[96:99], v252 offset:11264
	s_add_i32 s10, s26, 1
	s_lshr_b32 s11, s26, 1
	s_add_i32 s11, s11, 1
	s_lshr_b64 s[12:13], s[98:99], s11
	s_ff1_i32_b64 s14, s[12:13]
	s_cmp_lt_i32 s14, 0
	s_cselect_b32 s14, 0, s14
	s_add_i32 s14, s14, s11
	s_lshl_b32 s14, s14, 1
	s_bitcmp1_b32 s26, 0
	s_cselect_b32 s10, s14, s10
	s_sub_i32 s10, s10, s26
	s_lshl_b32 s10, s10, 12
	s_add_i32 s10, s10, 0xfffff400
	v_add_co_u32_e32 v248, vcc, s10, v138
	s_nop 1
	v_addc_co_u32_e32 v249, vcc, 0, v139, vcc
	v_add_co_u32_e32 v250, vcc, 0xff000000, v248
	s_nop 1
	v_addc_co_u32_e32 v251, vcc, -1, v249, vcc
	v_add_u32_e32 v180, s80, v131
	v_add_u32_e32 v200, -1, v180
	v_add_u32_e32 v204, 2, v152
	v_add_u32_e32 v205, -2, v180
	v_add_u32_e32 v206, 3, v152
	v_cvt_f32_i32_e32 v223, v200
	v_cmp_le_i32_e64 s[12:13], v204, v134
	v_cvt_f32_i32_e32 v224, v205
	v_cmp_le_i32_e64 s[14:15], v206, v134
	v_cmp_le_i32_e32 vcc, v152, v134
	v_cvt_f32_i32_e32 v222, v180
	v_cmp_lt_i32_e64 s[6:7], v152, v134
	v_add_u32_e32 v208, -3, v180
	v_add_u32_e32 v209, 4, v152
	v_add_u32_e32 v210, -4, v180
	v_add_u32_e32 v211, 5, v152
	v_add_u32_e32 v212, -5, v180
	v_add_u32_e32 v213, 6, v152
	v_add_u32_e32 v214, -6, v180
	v_add_u32_e32 v152, 7, v152
	v_add_u32_e32 v180, -7, v180
	v_cvt_f32_i32_e32 v227, v212
	v_cvt_f32_i32_e32 v228, v214
	v_cmp_le_i32_e64 s[24:25], v152, v134
	v_cvt_f32_i32_e32 v152, v180
	v_cmp_le_i32_e64 s[16:17], v209, v134
	v_cmp_le_i32_e64 s[20:21], v211, v134
	v_cmp_le_i32_e64 s[22:23], v213, v134
	s_and_b64 s[18:19], s[8:9], vcc
	s_and_b64 s[10:11], s[8:9], s[6:7]
	s_and_b64 s[12:13], s[8:9], s[12:13]
	s_and_b64 s[14:15], s[8:9], s[14:15]
	s_and_b64 s[16:17], s[8:9], s[16:17]
	s_and_b64 vcc, s[8:9], s[20:21]
	s_and_b64 s[6:7], s[8:9], s[22:23]
	s_and_b64 s[8:9], s[24:25], s[8:9]
	v_cvt_f32_i32_e32 v225, v208
	v_cvt_f32_i32_e32 v226, v210
	s_waitcnt lgkmcnt(0)
	s_add_i32 m0, s79, 0x1000
	s_nop 0
	global_load_lds_dwordx4 v[250:251], off
	global_load_lds_dwordx4 v[250:251], off offset:1024
	global_load_lds_dwordx4 v[250:251], off offset:2048
	global_load_lds_dwordx4 v[250:251], off offset:3072
	s_add_i32 m0, s79, 0x2000
	s_nop 0
	global_load_lds_dwordx4 v[248:249], off
	global_load_lds_dwordx4 v[248:249], off offset:1024
	global_load_lds_dwordx4 v[248:249], off offset:2048
	global_load_lds_dwordx4 v[248:249], off offset:3072
	v_mfma_f32_16x16x32_bf16 v[196:199], v[124:127], v[0:3], 0
	v_mfma_f32_16x16x32_bf16 v[200:203], v[116:119], v[0:3], 0
	v_mfma_f32_16x16x32_bf16 v[204:207], v[124:127], v[8:11], 0
	v_mfma_f32_16x16x32_bf16 v[196:199], v[120:123], v[4:7], v[196:199]
	v_mfma_f32_16x16x32_bf16 v[200:203], v[112:115], v[4:7], v[200:203]
	v_mfma_f32_16x16x32_bf16 v[204:207], v[120:123], v[12:15], v[204:207]
	s_nop 4
	v_add_f32_e32 v180, 0xc1800000, v196
	v_add_f32_e32 v196, 0xc1800000, v197
	v_add_f32_e32 v197, 0xc1800000, v198
	v_add_f32_e32 v198, 0xc1800000, v199
	v_add_f32_e32 v199, 0xc1800000, v200
	v_add_f32_e32 v200, 0xc1800000, v201
	v_add_f32_e32 v201, 0xc1800000, v202
	v_add_f32_e32 v202, 0xc1800000, v203
	v_add_f32_e32 v203, 0xc1800000, v204
	v_fma_f32 v200, -v170, v227, v200
	v_fma_f32 v201, -v170, v228, v201
	v_fma_f32 v202, -v170, v152, v202
	v_fma_f32 v203, -v171, v222, v203
	v_exp_f32_e32 v200, v200
	v_exp_f32_e32 v201, v201
	v_exp_f32_e32 v202, v202
	v_exp_f32_e32 v203, v203
	v_add_f32_e32 v204, 0xc1800000, v205
	v_fma_f32 v204, -v171, v223, v204
	v_exp_f32_e32 v208, v204
	v_cndmask_b32_e32 v217, 0, v200, vcc
	v_cndmask_b32_e64 v219, 0, v201, s[6:7]
	v_cndmask_b32_e64 v221, 0, v202, s[8:9]
	v_cndmask_b32_e64 v204, 0, v203, s[18:19]
	v_mfma_f32_16x16x32_bf16 v[200:203], v[116:119], v[8:11], 0
	v_fma_f32 v180, -v170, v222, v180
	v_exp_f32_e32 v180, v180
	v_add_f32_e32 v206, 0xc1800000, v206
	v_mfma_f32_16x16x32_bf16 v[200:203], v[112:115], v[12:15], v[200:203]
	v_fma_f32 v196, -v170, v223, v196
	v_cndmask_b32_e64 v205, 0, v180, s[18:19]
	v_fma_f32 v180, -v171, v224, v206
	v_exp_f32_e32 v180, v180
	v_fma_f32 v197, -v170, v224, v197
	s_nop 2
	v_add_f32_e32 v200, 0xc1800000, v200
	v_fma_f32 v200, -v171, v226, v200
	v_exp_f32_e32 v200, v200
	v_cndmask_b32_e64 v210, 0, v180, s[12:13]
	v_add_f32_e32 v180, 0xc1800000, v201
	v_add_f32_e32 v201, 0xc1800000, v203
	v_cndmask_b32_e64 v214, 0, v200, s[16:17]
	v_add_f32_e32 v200, 0xc1800000, v202
	v_fma_f32 v200, -v171, v228, v200
	v_fma_f32 v201, -v171, v152, v201
	v_fma_f32 v198, -v170, v225, v198
	v_exp_f32_e32 v196, v196
	v_add_f32_e32 v206, 0xc1800000, v207
	v_exp_f32_e32 v200, v200
	v_exp_f32_e32 v201, v201
	v_fma_f32 v199, -v170, v226, v199
	v_exp_f32_e32 v197, v197
	v_exp_f32_e32 v198, v198
	v_fma_f32 v206, -v171, v225, v206
	v_exp_f32_e32 v199, v199
	v_exp_f32_e32 v206, v206
	v_fma_f32 v180, -v171, v227, v180
	v_exp_f32_e32 v180, v180
	v_cndmask_b32_e64 v209, 0, v196, s[10:11]
	v_cndmask_b32_e64 v208, 0, v208, s[10:11]
	v_cndmask_b32_e64 v218, 0, v200, s[6:7]
	v_cndmask_b32_e64 v220, 0, v201, s[8:9]
	v_add_f32_e32 v200, 0, v204
	v_add_f32_e32 v201, 0, v205
	v_cndmask_b32_e64 v211, 0, v197, s[12:13]
	v_cndmask_b32_e64 v213, 0, v198, s[14:15]
	v_cvt_pk_bf16_f32 v196, v205, v209
	v_cvt_pk_bf16_f32 v197, v211, v213
	v_add_f32_e32 v200, v208, v200
	v_add_f32_e32 v201, v209, v201
	v_cndmask_b32_e64 v215, 0, v199, s[16:17]
	v_cvt_pk_bf16_f32 v198, v215, v217
	v_cvt_pk_bf16_f32 v199, v219, v221
	v_cndmask_b32_e64 v212, 0, v206, s[14:15]
	v_mfma_f32_16x16x32_bf16 v[92:95], v[108:111], v[196:199], v[92:95]
	v_add_f32_e64 v200, v210, v200
	v_add_f32_e64 v201, v211, v201
	v_cndmask_b32_e32 v216, 0, v180, vcc
	v_mfma_f32_16x16x32_bf16 v[88:91], v[104:107], v[196:199], v[88:91]
	v_mfma_f32_16x16x32_bf16 v[84:87], v[100:103], v[196:199], v[84:87]
	v_mfma_f32_16x16x32_bf16 v[80:83], v[96:99], v[196:199], v[80:83]
	v_cvt_pk_bf16_f32 v196, v204, v208
	v_cvt_pk_bf16_f32 v197, v210, v212
	v_cvt_pk_bf16_f32 v198, v214, v216
	v_cvt_pk_bf16_f32 v199, v218, v220
	s_nop 0
	v_mfma_f32_16x16x32_bf16 v[76:79], v[108:111], v[196:199], v[76:79]
	v_mfma_f32_16x16x32_bf16 v[72:75], v[104:107], v[196:199], v[72:75]
	v_mfma_f32_16x16x32_bf16 v[68:71], v[100:103], v[196:199], v[68:71]
	v_mfma_f32_16x16x32_bf16 v[64:67], v[96:99], v[196:199], v[64:67]
	v_add_f32_e64 v196, v212, v200
	v_add_f32_e64 v197, v213, v201
	v_add_f32_e32 v196, v214, v196
	v_add_f32_e32 v197, v215, v197
	s_nop 0
	v_add_f32_e32 v200, v216, v196
	v_add_f32_e32 v201, v217, v197
	v_mfma_f32_16x16x32_bf16 v[196:199], v[124:127], v[16:19], 0
	v_add_f32_e64 v200, v218, v200
	v_add_f32_e64 v201, v219, v201
	v_add_f32_e32 v200, v220, v200
	v_add_f32_e32 v201, v221, v201
	v_mfma_f32_16x16x32_bf16 v[196:199], v[120:123], v[20:23], v[196:199]
	v_add_f32_e64 v146, v146, v200
	v_add_f32_e64 v147, v147, v201
	v_mfma_f32_16x16x32_bf16 v[200:203], v[116:119], v[16:19], 0
	v_mfma_f32_16x16x32_bf16 v[124:127], v[124:127], v[24:27], 0
	s_nop 3
	v_add_f32_e32 v180, 0xc1800000, v196
	v_add_f32_e32 v196, 0xc1800000, v197
	v_fma_f32 v196, -v172, v223, v196
	v_exp_f32_e32 v204, v196
	v_add_f32_e32 v196, 0xc1800000, v198
	v_mfma_f32_16x16x32_bf16 v[116:119], v[116:119], v[24:27], 0
	v_fma_f32 v196, -v172, v224, v196
	v_exp_f32_e32 v205, v196
	v_add_f32_e32 v196, 0xc1800000, v199
	v_fma_f32 v196, -v172, v225, v196
	v_exp_f32_e32 v206, v196
	v_mfma_f32_16x16x32_bf16 v[196:199], v[112:115], v[20:23], v[200:203]
	v_fma_f32 v180, -v172, v222, v180
	v_exp_f32_e32 v180, v180
	v_cndmask_b32_e64 v205, 0, v205, s[12:13]
	v_mfma_f32_16x16x32_bf16 v[120:123], v[120:123], v[28:31], v[124:127]
	v_cndmask_b32_e64 v203, 0, v204, s[10:11]
	s_nop 2
	v_add_f32_e32 v196, 0xc1800000, v196
	v_add_f32_e32 v197, 0xc1800000, v197
	v_mfma_f32_16x16x32_bf16 v[112:115], v[112:115], v[28:31], v[116:119]
	v_add_f32_e32 v198, 0xc1800000, v198
	v_add_f32_e32 v120, 0xc1800000, v120
	v_fma_f32 v120, -v173, v222, v120
	v_exp_f32_e32 v120, v120
	v_add_f32_e32 v199, 0xc1800000, v199
	s_nop 2
	v_add_f32_e32 v112, 0xc1800000, v112
	v_fma_f32 v112, -v173, v226, v112
	v_exp_f32_e32 v112, v112
	v_cndmask_b32_e64 v200, 0, v120, s[18:19]
	v_add_f32_e32 v120, 0xc1800000, v121
	v_add_f32_e32 v121, 0xc1800000, v122
	v_add_f32_e32 v122, 0xc1800000, v123
	v_cndmask_b32_e64 v208, 0, v112, s[16:17]
	v_add_f32_e32 v112, 0xc1800000, v113
	v_add_f32_e32 v113, 0xc1800000, v114
	v_add_f32_e32 v114, 0xc1800000, v115
	v_fma_f32 v196, -v172, v226, v196
	v_fma_f32 v197, -v172, v227, v197
	v_fma_f32 v198, -v172, v228, v198
	v_fma_f32 v199, -v172, v152, v199
	v_fma_f32 v120, -v173, v223, v120
	v_fma_f32 v121, -v173, v224, v121
	v_fma_f32 v122, -v173, v225, v122
	v_fma_f32 v112, -v173, v227, v112
	v_fma_f32 v113, -v173, v228, v113
	v_fma_f32 v114, -v173, v152, v114
	v_exp_f32_e32 v196, v196
	v_exp_f32_e32 v197, v197
	v_exp_f32_e32 v198, v198
	v_exp_f32_e32 v199, v199
	v_exp_f32_e32 v120, v120
	v_exp_f32_e32 v121, v121
	v_exp_f32_e32 v122, v122
	v_exp_f32_e32 v112, v112
	v_exp_f32_e32 v113, v113
	v_exp_f32_e32 v114, v114
	v_cndmask_b32_e64 v201, 0, v180, s[18:19]
	v_cndmask_b32_e64 v207, 0, v206, s[14:15]
	v_cndmask_b32_e64 v209, 0, v196, s[16:17]
	v_cndmask_b32_e32 v211, 0, v197, vcc
	v_cndmask_b32_e64 v213, 0, v198, s[6:7]
	v_cndmask_b32_e64 v215, 0, v199, s[8:9]
	v_cvt_pk_bf16_f32 v196, v201, v203
	v_cvt_pk_bf16_f32 v197, v205, v207
	v_cvt_pk_bf16_f32 v198, v209, v211
	v_cvt_pk_bf16_f32 v199, v213, v215
	v_cndmask_b32_e64 v202, 0, v120, s[10:11]
	v_cndmask_b32_e64 v204, 0, v121, s[12:13]
	v_cndmask_b32_e64 v206, 0, v122, s[14:15]
	v_mfma_f32_16x16x32_bf16 v[60:63], v[108:111], v[196:199], v[60:63]
	v_cndmask_b32_e32 v210, 0, v112, vcc
	v_cndmask_b32_e64 v212, 0, v113, s[6:7]
	v_cndmask_b32_e64 v214, 0, v114, s[8:9]
	v_cvt_pk_bf16_f32 v112, v200, v202
	v_cvt_pk_bf16_f32 v113, v204, v206
	v_cvt_pk_bf16_f32 v114, v208, v210
	v_cvt_pk_bf16_f32 v115, v212, v214
	v_mfma_f32_16x16x32_bf16 v[56:59], v[104:107], v[196:199], v[56:59]
	v_mfma_f32_16x16x32_bf16 v[44:47], v[108:111], v[112:115], v[44:47]
	v_add_f32_e64 v108, v200, 0
	v_add_f32_e64 v109, v201, 0
	v_add_f32_e32 v108, v202, v108
	v_add_f32_e32 v109, v203, v109
	v_mfma_f32_16x16x32_bf16 v[40:43], v[104:107], v[112:115], v[40:43]
	v_add_f32_e64 v108, v204, v108
	v_add_f32_e64 v109, v205, v109
	v_add_f32_e32 v104, v206, v108
	v_add_f32_e32 v105, v207, v109
	v_mfma_f32_16x16x32_bf16 v[52:55], v[100:103], v[196:199], v[52:55]
	v_add_f32_e64 v104, v208, v104
	v_add_f32_e64 v105, v209, v105
	v_add_f32_e32 v104, v210, v104
	v_add_f32_e32 v105, v211, v105
	v_mfma_f32_16x16x32_bf16 v[48:51], v[96:99], v[196:199], v[48:51]
	v_mfma_f32_16x16x32_bf16 v[36:39], v[100:103], v[112:115], v[36:39]
	v_add_f32_e64 v100, v212, v104
	v_add_f32_e64 v101, v213, v105
	v_add_f32_e32 v100, v214, v100
	v_add_f32_e32 v101, v215, v101
	v_mfma_f32_16x16x32_bf16 v[32:35], v[96:99], v[112:115], v[32:35]
	v_add_f32_e64 v142, v142, v100
	v_add_f32_e64 v143, v143, v101
	s_branch .LBB0_397

.LBB0_402:
	v_add_u32_e32 v128, -7, v211
	v_add_co_u32_e32 v250, vcc, 0xff000400, v144
	s_nop 1
	v_addc_co_u32_e32 v251, vcc, -1, v145, vcc
	v_add_co_u32_e32 v248, vcc, 0x400, v144
	s_nop 1
	v_addc_co_u32_e32 v249, vcc, 0, v145, vcc
	s_waitcnt vmcnt(0)
	ds_read_b128 v[120:123], v252 offset:4096
	ds_read_b128 v[124:127], v252 offset:5120
	ds_read_b128 v[116:119], v252 offset:6144
	ds_read_b128 v[112:115], v252 offset:7168
	ds_read_b128 v[96:99], v252 offset:8192
	ds_read_b128 v[100:103], v252 offset:9216
	ds_read_b128 v[104:107], v252 offset:10240
	ds_read_b128 v[108:111], v252 offset:11264
	v_add_u32_e32 v129, 7, v210
	v_cmp_le_i32_e32 vcc, v128, v134
	v_cmp_gt_i32_e64 s[6:7], s91, v129
	s_and_b64 s[12:13], vcc, s[6:7]
	v_cmp_lt_i32_e32 vcc, v128, v134
	v_add_u32_e32 v128, 6, v210
	v_cmp_gt_i32_e64 s[6:7], s91, v128
	v_cvt_f32_i32_e32 v150, v128
	v_add_u32_e32 v128, -5, v211
	s_and_b64 s[14:15], vcc, s[6:7]
	v_cmp_le_i32_e32 vcc, v128, v134
	v_add_u32_e32 v128, 5, v210
	v_cmp_gt_i32_e64 s[6:7], s91, v128
	v_cvt_f32_i32_e32 v158, v128
	v_add_u32_e32 v128, -4, v211
	s_and_b64 s[16:17], vcc, s[6:7]
	v_cmp_le_i32_e32 vcc, v128, v134
	v_add_u32_e32 v128, 4, v210
	v_cmp_gt_i32_e64 s[6:7], s91, v128
	v_cvt_f32_i32_e32 v212, v128
	v_add_u32_e32 v128, -3, v211
	s_and_b64 s[18:19], vcc, s[6:7]
	v_cmp_le_i32_e32 vcc, v128, v134
	v_add_u32_e32 v128, 3, v210
	v_cmp_gt_i32_e64 s[6:7], s91, v128
	v_cvt_f32_i32_e32 v148, v128
	v_add_u32_e32 v128, -2, v211
	s_and_b64 s[10:11], vcc, s[6:7]
	v_cmp_le_i32_e32 vcc, v128, v134
	v_add_u32_e32 v128, 2, v210
	v_cmp_gt_i32_e64 s[6:7], s91, v128
	v_cvt_f32_i32_e32 v154, v128
	v_add_u32_e32 v128, -1, v211
	s_and_b64 s[8:9], vcc, s[6:7]
	v_cmp_le_i32_e32 vcc, v128, v134
	v_add_u32_e32 v128, 1, v210
	v_cvt_f32_i32_e32 v146, v129
	v_cmp_gt_i32_e64 s[6:7], s91, v128
	v_cvt_f32_i32_e32 v152, v128
	v_cvt_f32_i32_e32 v132, v210
	s_and_b64 s[6:7], vcc, s[6:7]
	v_cmp_le_i32_e32 vcc, v211, v134
	v_cmp_gt_i32_e64 s[20:21], s91, v210
	s_and_b64 vcc, vcc, s[20:21]
	s_add_i32 s0, s0, 1
	v_subrev_u32_e32 v210, 32, v210
	v_add_u32_e32 v211, 32, v211
	v_lshl_add_u64 v[144:145], v[144:145], 0, s[52:53]
	s_cmp_lt_u32 s0, s71
	s_waitcnt lgkmcnt(0)
	s_mov_b32 m0, s98
	s_nop 0
	global_load_lds_dwordx4 v[250:251], off
	global_load_lds_dwordx4 v[250:251], off offset:1024
	global_load_lds_dwordx4 v[250:251], off offset:2048
	global_load_lds_dwordx4 v[250:251], off offset:3072
	s_mov_b32 m0, s99
	s_nop 0
	global_load_lds_dwordx4 v[248:249], off
	global_load_lds_dwordx4 v[248:249], off offset:1024
	global_load_lds_dwordx4 v[248:249], off offset:2048
	global_load_lds_dwordx4 v[248:249], off offset:3072
	v_mfma_f32_16x16x32_bf16 v[128:131], v[120:123], v[0:3], 0
	v_mfma_f32_16x16x32_bf16 v[128:131], v[124:127], v[4:7], v[128:131]
	v_mfma_f32_16x16x32_bf16 v[214:217], v[120:123], v[8:11], 0
	v_mfma_f32_16x16x32_bf16 v[214:217], v[124:127], v[12:15], v[214:217]
	s_nop 5
	v_add_f32_e32 v128, 0xc1800000, v128
	v_fma_f32 v128, -v170, v146, v128
	v_exp_f32_e32 v147, v128
	v_add_f32_e32 v128, 0xc1800000, v129
	v_fma_f32 v128, -v170, v150, v128
	v_exp_f32_e32 v149, v128
	v_cndmask_b32_e64 v157, 0, v147, s[12:13]
	v_add_f32_e32 v147, 0xc1800000, v214
	v_fma_f32 v147, -v171, v146, v147
	v_exp_f32_e32 v147, v147
	v_add_f32_e32 v128, 0xc1800000, v130
	v_fma_f32 v128, -v170, v158, v128
	v_exp_f32_e32 v151, v128
	v_cndmask_b32_e64 v156, 0, v147, s[12:13]
	v_add_f32_e32 v147, 0xc1800000, v215
	v_fma_f32 v147, -v171, v150, v147
	v_exp_f32_e32 v147, v147
	v_add_f32_e32 v128, 0xc1800000, v131
	v_fma_f32 v128, -v170, v212, v128
	v_exp_f32_e32 v153, v128
	v_cndmask_b32_e64 v160, 0, v147, s[14:15]
	v_add_f32_e32 v147, 0xc1800000, v216
	v_fma_f32 v147, -v171, v158, v147
	v_exp_f32_e32 v147, v147
	v_cndmask_b32_e64 v161, 0, v149, s[14:15]
	v_add_f32_e32 v230, 0, v156
	v_add_f32_e32 v231, 0, v157
	v_cndmask_b32_e64 v219, 0, v151, s[16:17]
	v_cndmask_b32_e64 v218, 0, v147, s[16:17]
	v_add_f32_e32 v147, 0xc1800000, v217
	v_fma_f32 v147, -v171, v212, v147
	v_exp_f32_e32 v147, v147
	v_add_f32_e32 v214, v160, v230
	v_add_f32_e32 v215, v161, v231
	v_cndmask_b32_e64 v221, 0, v153, s[18:19]
	v_add_f32_e32 v214, v218, v214
	v_add_f32_e32 v215, v219, v215
	v_cndmask_b32_e64 v220, 0, v147, s[18:19]
	v_add_f32_e32 v230, v220, v214
	v_add_f32_e32 v231, v221, v215
	v_mfma_f32_16x16x32_bf16 v[214:217], v[116:119], v[8:11], 0
	v_mfma_f32_16x16x32_bf16 v[214:217], v[112:115], v[12:15], v[214:217]
	v_mfma_f32_16x16x32_bf16 v[128:131], v[116:119], v[0:3], 0
	v_mfma_f32_16x16x32_bf16 v[128:131], v[112:115], v[4:7], v[128:131]
	s_nop 5
	v_add_f32_e32 v147, 0xc1800000, v214
	v_fma_f32 v147, -v171, v148, v147
	v_exp_f32_e32 v147, v147
	s_nop 0
	v_cndmask_b32_e64 v222, 0, v147, s[10:11]
	v_add_f32_e32 v147, 0xc1800000, v215
	v_fma_f32 v147, -v171, v154, v147
	v_exp_f32_e32 v147, v147
	v_add_f32_e32 v128, 0xc1800000, v128
	v_add_f32_e32 v129, 0xc1800000, v129
	v_add_f32_e32 v130, 0xc1800000, v130
	v_cndmask_b32_e64 v224, 0, v147, s[8:9]
	v_add_f32_e32 v147, 0xc1800000, v216
	v_fma_f32 v147, -v171, v152, v147
	v_exp_f32_e32 v147, v147
	v_add_f32_e32 v131, 0xc1800000, v131
	v_fma_f32 v128, -v170, v148, v128
	v_fma_f32 v129, -v170, v154, v129
	v_fma_f32 v130, -v170, v152, v130
	v_fma_f32 v131, -v170, v132, v131
	v_cndmask_b32_e64 v226, 0, v147, s[6:7]
	v_add_f32_e32 v147, 0xc1800000, v217
	v_exp_f32_e32 v128, v128
	v_exp_f32_e32 v129, v129
	v_exp_f32_e32 v130, v130
	v_exp_f32_e32 v131, v131
	v_fma_f32 v147, -v171, v132, v147
	v_exp_f32_e32 v147, v147
	v_cndmask_b32_e64 v223, 0, v128, s[10:11]
	v_cndmask_b32_e64 v225, 0, v129, s[8:9]
	v_cndmask_b32_e64 v227, 0, v130, s[6:7]
	v_cndmask_b32_e32 v229, 0, v131, vcc
	v_cvt_pk_bf16_f32 v128, v157, v161
	v_cvt_pk_bf16_f32 v129, v219, v221
	v_cvt_pk_bf16_f32 v130, v223, v225
	v_cvt_pk_bf16_f32 v131, v227, v229
	v_cndmask_b32_e32 v228, 0, v147, vcc
	v_mfma_f32_16x16x32_bf16 v[80:83], v[96:99], v[128:131], v[80:83]
	v_add_f32_e64 v230, v222, v230
	v_add_f32_e64 v231, v223, v231
	v_add_f32_e32 v214, v224, v230
	v_add_f32_e32 v215, v225, v231
	v_mfma_f32_16x16x32_bf16 v[84:87], v[100:103], v[128:131], v[84:87]
	v_add_f32_e64 v214, v226, v214
	v_add_f32_e64 v215, v227, v215
	v_add_f32_e32 v214, v228, v214
	v_add_f32_e32 v215, v229, v215
	v_mfma_f32_16x16x32_bf16 v[88:91], v[104:107], v[128:131], v[88:91]
	v_add_f32_e64 v138, v138, v214
	v_add_f32_e64 v139, v139, v215
	v_mfma_f32_16x16x32_bf16 v[92:95], v[108:111], v[128:131], v[92:95]
	v_cvt_pk_bf16_f32 v128, v156, v160
	v_cvt_pk_bf16_f32 v129, v218, v220
	v_cvt_pk_bf16_f32 v130, v222, v224
	v_cvt_pk_bf16_f32 v131, v226, v228
	s_nop 0
	v_mfma_f32_16x16x32_bf16 v[64:67], v[96:99], v[128:131], v[64:67]
	v_mfma_f32_16x16x32_bf16 v[68:71], v[100:103], v[128:131], v[68:71]
	v_mfma_f32_16x16x32_bf16 v[72:75], v[104:107], v[128:131], v[72:75]
	v_mfma_f32_16x16x32_bf16 v[76:79], v[108:111], v[128:131], v[76:79]
	v_mfma_f32_16x16x32_bf16 v[128:131], v[120:123], v[16:19], 0
	v_mfma_f32_16x16x32_bf16 v[128:131], v[124:127], v[20:23], v[128:131]
	v_mfma_f32_16x16x32_bf16 v[120:123], v[120:123], v[24:27], 0
	v_mfma_f32_16x16x32_bf16 v[120:123], v[124:127], v[28:31], v[120:123]
	s_nop 5
	v_add_f32_e32 v128, 0xc1800000, v128
	v_fma_f32 v128, -v172, v146, v128
	v_exp_f32_e32 v147, v128
	v_add_f32_e32 v128, 0xc1800000, v129
	v_fma_f32 v128, -v172, v150, v128
	v_exp_f32_e32 v149, v128
	v_add_f32_e32 v128, 0xc1800000, v130
	v_fma_f32 v128, -v172, v158, v128
	v_exp_f32_e32 v151, v128
	v_add_f32_e32 v128, 0xc1800000, v131
	v_fma_f32 v128, -v172, v212, v128
	v_exp_f32_e32 v153, v128
	v_mfma_f32_16x16x32_bf16 v[128:131], v[116:119], v[16:19], 0
	v_add_f32_e32 v120, 0xc1800000, v120
	v_fma_f32 v120, -v173, v146, v120
	v_exp_f32_e32 v120, v120
	v_mfma_f32_16x16x32_bf16 v[116:119], v[116:119], v[24:27], 0
	v_add_f32_e32 v122, 0xc1800000, v122
	v_fma_f32 v122, -v173, v158, v122
	v_exp_f32_e32 v122, v122
	v_mfma_f32_16x16x32_bf16 v[128:131], v[112:115], v[20:23], v[128:131]
	v_cndmask_b32_e64 v156, 0, v120, s[12:13]
	v_add_f32_e32 v120, 0xc1800000, v121
	v_fma_f32 v120, -v173, v150, v120
	v_mfma_f32_16x16x32_bf16 v[112:115], v[112:115], v[28:31], v[116:119]
	v_exp_f32_e32 v120, v120
	v_cndmask_b32_e64 v146, 0, v122, s[16:17]
	v_add_f32_e32 v122, 0xc1800000, v123
	s_nop 0
	v_add_f32_e32 v128, 0xc1800000, v128
	v_fma_f32 v122, -v173, v212, v122
	s_nop 1
	v_add_f32_e32 v112, 0xc1800000, v112
	v_fma_f32 v112, -v173, v148, v112
	v_exp_f32_e32 v112, v112
	v_add_f32_e32 v114, 0xc1800000, v114
	v_fma_f32 v114, -v173, v152, v114
	v_exp_f32_e32 v114, v114
	v_fma_f32 v128, -v172, v148, v128
	v_add_f32_e32 v129, 0xc1800000, v129
	v_exp_f32_e32 v122, v122
	v_cndmask_b32_e64 v148, 0, v112, s[10:11]
	v_add_f32_e32 v112, 0xc1800000, v113
	v_exp_f32_e32 v128, v128
	v_fma_f32 v129, -v172, v154, v129
	v_add_f32_e32 v130, 0xc1800000, v130
	v_cndmask_b32_e64 v157, 0, v147, s[12:13]
	v_fma_f32 v112, -v173, v154, v112
	v_exp_f32_e32 v129, v129
	v_fma_f32 v130, -v172, v152, v130
	v_add_f32_e32 v131, 0xc1800000, v131
	v_cndmask_b32_e64 v161, 0, v149, s[14:15]
	v_add_f32_e32 v124, 0, v156
	v_add_f32_e32 v125, 0, v157
	v_cndmask_b32_e64 v160, 0, v120, s[14:15]
	v_exp_f32_e32 v112, v112
	v_cndmask_b32_e64 v152, 0, v114, s[6:7]
	v_add_f32_e32 v114, 0xc1800000, v115
	v_exp_f32_e32 v130, v130
	v_fma_f32 v131, -v172, v132, v131
	v_cndmask_b32_e64 v147, 0, v151, s[16:17]
	v_add_f32_e32 v120, v160, v124
	v_add_f32_e32 v121, v161, v125
	v_fma_f32 v114, -v173, v132, v114
	v_exp_f32_e32 v131, v131
	v_cndmask_b32_e64 v151, 0, v153, s[18:19]
	v_add_f32_e32 v120, v146, v120
	v_add_f32_e32 v121, v147, v121
	v_cndmask_b32_e64 v150, 0, v122, s[18:19]
	v_exp_f32_e32 v114, v114
	v_cndmask_b32_e64 v149, 0, v128, s[10:11]
	v_add_f32_e32 v120, v150, v120
	v_add_f32_e32 v121, v151, v121
	v_cndmask_b32_e64 v155, 0, v129, s[8:9]
	v_add_f32_e32 v116, v148, v120
	v_add_f32_e32 v117, v149, v121
	v_cndmask_b32_e64 v154, 0, v112, s[8:9]
	v_cndmask_b32_e64 v153, 0, v130, s[6:7]
	v_add_f32_e32 v112, v154, v116
	v_add_f32_e32 v113, v155, v117
	v_cndmask_b32_e32 v159, 0, v131, vcc
	v_add_f32_e32 v112, v152, v112
	v_add_f32_e32 v113, v153, v113
	v_cndmask_b32_e32 v158, 0, v114, vcc
	v_add_f32_e32 v112, v158, v112
	v_add_f32_e32 v113, v159, v113
	v_cvt_pk_bf16_f32 v128, v157, v161
	v_cvt_pk_bf16_f32 v129, v147, v151
	v_cvt_pk_bf16_f32 v130, v149, v155
	v_cvt_pk_bf16_f32 v131, v153, v159
	v_cvt_pk_bf16_f32 v114, v148, v154
	s_nop 0
	v_add_f32_e32 v142, v142, v112
	v_add_f32_e32 v143, v143, v113
	v_mfma_f32_16x16x32_bf16 v[48:51], v[96:99], v[128:131], v[48:51]
	v_cvt_pk_bf16_f32 v112, v156, v160
	v_cvt_pk_bf16_f32 v113, v146, v150
	v_cvt_pk_bf16_f32 v115, v152, v158
	v_mfma_f32_16x16x32_bf16 v[52:55], v[100:103], v[128:131], v[52:55]
	v_mfma_f32_16x16x32_bf16 v[56:59], v[104:107], v[128:131], v[56:59]
	v_mfma_f32_16x16x32_bf16 v[60:63], v[108:111], v[128:131], v[60:63]
	v_mfma_f32_16x16x32_bf16 v[32:35], v[96:99], v[112:115], v[32:35]
	v_mfma_f32_16x16x32_bf16 v[36:39], v[100:103], v[112:115], v[36:39]
	v_mfma_f32_16x16x32_bf16 v[44:47], v[104:107], v[112:115], v[44:47]
	v_mfma_f32_16x16x32_bf16 v[40:43], v[108:111], v[112:115], v[40:43]
	s_cbranch_scc1 .LBB0_402
	s_branch .LBB0_369
